# plus R phase: b_router loaded once per token block; four partial-logit LDS reads issued together
# speedup vs baseline: 1.0021x; 1.0021x over previous
.LBB0_794:
	s_or_b64 exec, exec, s[2:3]
	s_mov_b64 s[2:3], s[0:1]
	s_waitcnt lgkmcnt(0)
	s_barrier
	s_getreg_b32 s4, hwreg(HW_REG_HW_ID, 0, 6)
	s_and_b32 s4, s4, 63
	s_lshl_b32 s4, s4, 2
	s_or_b32 s4, s4, 0x20100
	v_mov_b32_e32 v0, s4
	ds_read_b32 v0, v0
	s_mov_b64 s[4:5], s[0:1]
	s_mov_b64 s[10:11], s[0:1]
	s_mov_b64 s[6:7], s[0:1]
	s_waitcnt lgkmcnt(0)
	v_readfirstlane_b32 s15, v0
	v_mov_b32_e32 v0, v213
	v_readlane_b32 s8, v254, 16
	v_mbcnt_lo_u32_b32 v0, -1, v0
	s_lshl_b32 s14, s15, 6
	v_mbcnt_hi_u32_b32 v0, -1, v0
	v_readlane_b32 s9, v254, 17
	s_lshl_b32 s38, s67, 16
	v_add_u32_e32 v128, s14, v0
	s_andn2_b64 vcc, exec, s[8:9]
	s_cbranch_vccnz .LBB0_817
	s_load_dwordx2 s[8:9], s[2:3], 0x98
	s_nop 0
	s_load_dwordx2 s[2:3], s[4:5], 0x40
	s_nop 0
	s_load_dwordx2 s[4:5], s[10:11], 0x48
	s_lshl_b32 s10, s38, 1
	s_load_dwordx2 s[22:23], s[6:7], 0x68
	s_waitcnt lgkmcnt(0)
	s_add_u32 s26, s8, s10
	s_addc_u32 s27, s9, 0
	s_add_u32 s24, s26, 0x100000
	s_addc_u32 s25, s27, 0
	s_add_u32 s10, s8, 0xc00000
	s_addc_u32 s11, s9, 0
	s_add_u32 s12, s8, 0x700000
	s_addc_u32 s13, s9, 0
	s_add_u32 s16, s8, 0x780000
	s_addc_u32 s17, s9, 0
	s_add_u32 s20, s8, 0x800000
	s_addc_u32 s21, s9, 0
	s_add_u32 s30, s8, 0x34000000
	s_addc_u32 s31, s9, 0
	v_and_b32_e32 v145, 15, v128
	v_bfe_u32 v134, v128, 4, 2
	s_lshl_b32 s6, s15, 7
	v_lshlrev_b32_e32 v212, 10, v145
	s_ashr_i32 s7, s6, 31
	v_lshlrev_b32_e32 v0, 3, v134
	v_or_b32_e32 v130, s6, v0
	v_mov_b32_e32 v131, s7
	v_or_b32_e32 v48, 0x4000, v212
	v_mov_b32_e32 v49, v213
	s_add_u32 s26, s26, 0x110000
	v_lshl_add_u64 v[0:1], v[130:131], 0, v[212:213]
	v_lshl_add_u64 v[2:3], v[130:131], 0, v[48:49]
	v_or_b32_e32 v16, 32, v130
	v_mov_b32_e32 v17, s7
	v_or_b32_e32 v24, 64, v130
	v_mov_b32_e32 v25, s7
	v_or_b32_e32 v54, 0x60, v130
	v_mov_b32_e32 v55, s7
	s_addc_u32 s27, s27, 0
	v_lshlrev_b64 v[0:1], 1, v[0:1]
	v_lshlrev_b64 v[8:9], 1, v[2:3]
	v_lshl_add_u64 v[18:19], v[16:17], 0, v[212:213]
	v_lshl_add_u64 v[16:17], v[16:17], 0, v[48:49]
	v_lshl_add_u64 v[26:27], v[24:25], 0, v[212:213]
	v_lshl_add_u64 v[34:35], v[24:25], 0, v[48:49]
	v_lshl_add_u64 v[56:57], v[54:55], 0, v[212:213]
	v_lshl_add_u64 v[58:59], v[54:55], 0, v[48:49]
	v_lshl_add_u64 v[44:45], s[24:25], 0, v[0:1]
	v_lshl_add_u64 v[0:1], s[26:27], 0, v[0:1]
	v_lshl_add_u64 v[50:51], s[26:27], 0, v[8:9]
	v_lshl_add_u64 v[18:19], v[18:19], 1, s[26:27]
	v_lshl_add_u64 v[20:21], v[16:17], 1, s[26:27]
	v_lshl_add_u64 v[32:33], v[26:27], 1, s[26:27]
	v_lshl_add_u64 v[36:37], v[34:35], 1, s[26:27]
	v_lshl_add_u64 v[56:57], v[56:57], 1, s[26:27]
	v_lshl_add_u64 v[60:61], v[58:59], 1, s[26:27]
	s_lshl_b32 s26, s67, 6
	s_mov_b32 s27, s39
	v_lshl_add_u64 v[52:53], s[24:25], 0, v[8:9]
	s_lshl_b32 s24, s67, 10
	s_lshl_b64 s[26:27], s[26:27], 2
	s_add_u32 s26, s8, s26
	s_addc_u32 s27, s9, s27
	s_lshl_b64 s[28:29], s[90:91], 2
	s_mov_b32 s25, s39
	s_add_u32 s22, s22, s28
	s_addc_u32 s23, s23, s29
	s_lshl_b64 s[24:25], s[24:25], 2
	s_add_u32 s4, s4, s24
	s_addc_u32 s5, s5, s25
	s_add_u32 s2, s2, s24
	s_waitcnt vmcnt(27)
	v_ashrrev_i32_e32 v65, 31, v130
	v_mov_b32_e32 v64, v130
	s_addc_u32 s3, s3, s25
	s_waitcnt vmcnt(25)
	v_lshlrev_b64 v[72:73], 2, v[64:65]
	v_lshl_add_u64 v[116:117], s[4:5], 0, v[72:73]
	v_lshl_add_u64 v[124:125], s[2:3], 0, v[72:73]
	global_load_dwordx4 v[0:3], v[0:1], off
	s_nop 0
	global_load_dwordx4 v[4:7], v[52:53], off
	global_load_dwordx4 v[8:11], v[44:45], off
	global_load_dwordx4 v[12:15], v[44:45], off offset:64
	s_nop 0
	global_load_dwordx4 v[16:19], v[18:19], off
	s_nop 0
	global_load_dwordx4 v[20:23], v[20:21], off
	s_nop 0
	global_load_dwordx4 v[24:27], v[52:53], off offset:64
	global_load_dwordx4 v[28:31], v[52:53], off offset:128
	s_nop 0
	global_load_dwordx4 v[32:35], v[32:33], off
	s_nop 0
	global_load_dwordx4 v[36:39], v[36:37], off
	s_nop 0
	global_load_dwordx4 v[40:43], v[44:45], off offset:128
	s_nop 0
	global_load_dwordx4 v[44:47], v[44:45], off offset:192
	s_nop 0
	global_load_dwordx4 v[48:51], v[50:51], off
	s_nop 0
	global_load_dwordx4 v[52:55], v[52:53], off offset:192
	s_nop 0
	global_load_dwordx4 v[56:59], v[56:57], off
	s_nop 0
	global_load_dwordx4 v[60:63], v[60:61], off
	s_nop 0
	global_load_dwordx4 v[64:67], v[116:117], off offset:384
	global_load_dwordx4 v[68:71], v[116:117], off offset:400
	global_load_dwordx4 v[72:75], v[124:125], off offset:384
	global_load_dwordx4 v[76:79], v[124:125], off offset:400
	global_load_dwordx4 v[80:83], v[116:117], off offset:256
	global_load_dwordx4 v[84:87], v[116:117], off offset:272
	global_load_dwordx4 v[88:91], v[124:125], off offset:256
	global_load_dwordx4 v[92:95], v[124:125], off offset:272
	global_load_dwordx4 v[96:99], v[116:117], off offset:128
	global_load_dwordx4 v[100:103], v[116:117], off offset:144
	global_load_dwordx4 v[104:107], v[124:125], off offset:128
	global_load_dwordx4 v[108:111], v[124:125], off offset:144
	global_load_dwordx4 v[112:115], v[116:117], off
	s_nop 0
	global_load_dwordx4 v[116:119], v[116:117], off offset:16
	s_nop 0
	global_load_dwordx4 v[120:123], v[124:125], off
	s_nop 0
	global_load_dwordx4 v[124:127], v[124:125], off offset:16
	s_lshl_b64 s[4:5], s[6:7], 1
	s_add_u32 s4, s8, s4
	s_addc_u32 s5, s9, s5
	v_and_b32_e32 v212, 48, v128
	v_and_b32_e32 v129, 63, v128
	v_lshlrev_b32_e32 v135, 2, v128
	v_lshl_add_u64 v[132:133], s[4:5], 0, v[212:213]
	s_mov_b64 s[4:5], 0x40000000
	s_cmp_eq_u32 s15, 0
	v_lshl_add_u64 v[146:147], v[132:133], 0, s[4:5]
	v_cmp_gt_u32_e64 s[4:5], 16, v129
	s_cselect_b64 s[6:7], -1, 0
	v_and_b32_e32 v212, 0x7c, v135
	v_add_u32_e32 v144, 0, v135
	v_lshlrev_b32_e32 v132, 2, v129
	s_and_b64 s[78:79], s[6:7], s[4:5]
	v_and_b32_e32 v129, 0x3fffffe0, v128
	v_add_u32_e32 v215, 0, v212
	s_add_i32 s6, s14, 0
	s_lshl_b32 s24, s15, 11
	v_lshl_add_u64 v[148:149], s[22:23], 0, v[212:213]
	global_load_dword v253, v[148:149], off
	v_lshl_add_u32 v216, v129, 2, v215
	v_add_u32_e32 v217, s6, v132
	s_movk_i32 s6, 0x80
	s_movk_i32 s22, 0x84
	v_mad_u64_u32 v[150:151], s[14:15], v128, 12, v[144:145]
	v_ashrrev_i32_e32 v129, 31, v128
	v_cmp_gt_i32_e64 s[2:3], 32, v128
	v_xor_b32_e32 v210, 64, v132
	v_xor_b32_e32 v211, 0x80, v132
	v_ashrrev_i32_e32 v136, 5, v128
	v_cmp_gt_i32_e64 s[6:7], s6, v128
	v_mul_lo_u32 v135, v128, s22
	v_mul_lo_u32 v137, v128, -12
	v_lshl_add_u64 v[132:133], v[128:129], 2, s[26:27]
	v_ashrrev_i32_e32 v151, 2, v128
	v_and_b32_e32 v218, 3, v128
	v_lshl_add_u64 v[128:129], s[8:9], 0, v[130:131]
	s_mov_b64 s[8:9], 0x50000000
	v_lshl_add_u64 v[154:155], v[128:129], 0, s[8:9]
	v_mul_lo_u32 v219, v136, s22
	v_readlane_b32 s8, v254, 46
	v_lshl_add_u32 v214, v145, 2, 0
	s_mov_b64 s[14:15], 0x1000
	v_add3_u32 v212, v219, v212, s8
	v_readlane_b32 s8, v254, 10
	v_lshl_add_u64 v[152:153], v[132:133], 0, s[14:15]
	v_lshl_add_u32 v132, v134, 9, v214
	v_add_u32_e32 v220, s8, v145
	v_readlane_b32 s8, v254, 41
	v_add_u32_e32 v221, 0, v135
	v_add_u32_e32 v222, s24, v132
	v_add_u32_e32 v223, v150, v137
	s_mov_b32 s14, s8
	v_readlane_b32 s9, v254, 42
	s_branch .LBB0_797

.LBB0_800:
	s_or_b64 exec, exec, s[8:9]
	v_pk_mul_f32 v[190:191], v[190:191], v[170:171] op_sel_hi:[1,0]
	v_lshlrev_b64 v[168:169], 10, v[158:159]
	v_pk_fma_f32 v[196:197], v[120:121], v[190:191], v[112:113]
	v_pk_mul_f32 v[190:191], v[192:193], v[170:171] op_sel_hi:[1,0]
	v_mul_f32_e32 v157, 4.0, v196
	v_mul_f32_e32 v159, 4.0, v197
	v_mov_b32_e32 v192, v213
	v_cvt_pk_fp8_f32 v192, v157, v159
	v_pk_mul_f32 v[188:189], v[188:189], v[170:171] op_sel_hi:[1,0]
	v_pk_mul_f32 v[194:195], v[194:195], v[170:171] op_sel_hi:[1,0]
	v_pk_fma_f32 v[198:199], v[122:123], v[188:189], v[114:115]
	v_pk_fma_f32 v[194:195], v[124:125], v[194:195], v[116:117]
	v_mul_f32_e32 v157, 4.0, v198
	v_mul_f32_e32 v159, 4.0, v199
	v_cvt_pk_fp8_f32 v192, v157, v159 op_sel:[0,0,1]
	v_mul_f32_e32 v157, 4.0, v194
	v_mul_f32_e32 v159, 4.0, v195
	v_mov_b32_e32 v193, v213
	v_cvt_pk_fp8_f32 v193, v157, v159
	v_pk_fma_f32 v[200:201], v[126:127], v[190:191], v[118:119]
	v_lshl_add_u64 v[168:169], v[154:155], 0, v[168:169]
	v_mul_f32_e32 v157, 4.0, v200
	v_mul_f32_e32 v159, 4.0, v201
	v_cvt_pk_fp8_f32 v193, v157, v159 op_sel:[0,0,1]
	v_cvt_pk_bf16_f32 v188, v196, v197
	v_cvt_pk_bf16_f32 v189, v198, v199
	v_cvt_pk_bf16_f32 v190, v194, v195
	global_store_dwordx2 v[168:169], v[192:193], off
	v_lshlrev_b32_e32 v192, 16, v188
	v_and_b32_e32 v193, 0xffff0000, v188
	v_cvt_pk_bf16_f32 v191, v200, v201
	v_pk_add_f32 v[192:193], v[196:197], v[192:193] neg_lo:[0,1] neg_hi:[0,1]
	v_lshlrev_b32_e32 v196, 16, v189
	v_and_b32_e32 v197, 0xffff0000, v189
	v_pk_add_f32 v[196:197], v[198:199], v[196:197] neg_lo:[0,1] neg_hi:[0,1]
	v_cvt_pk_bf16_f32 v192, v192, v193
	v_cvt_pk_bf16_f32 v193, v196, v197
	v_lshlrev_b32_e32 v196, 16, v190
	v_and_b32_e32 v197, 0xffff0000, v190
	v_pk_add_f32 v[194:195], v[194:195], v[196:197] neg_lo:[0,1] neg_hi:[0,1]
	v_lshlrev_b32_e32 v196, 16, v191
	v_and_b32_e32 v197, 0xffff0000, v191
	v_pk_add_f32 v[196:197], v[200:201], v[196:197] neg_lo:[0,1] neg_hi:[0,1]
	v_cvt_pk_bf16_f32 v194, v194, v195
	v_cvt_pk_bf16_f32 v195, v196, v197
	v_mfma_f32_16x16x32_bf16 v[196:199], v[188:191], v[8:11], 0
	v_mul_f32_e64 v182, v182, v170
	v_mul_f32_e64 v183, v183, v170
	v_pk_mul_f32 v[180:181], v[180:181], v[170:171] op_sel_hi:[1,0]
	v_pk_mul_f32 v[186:187], v[186:187], v[170:171] op_sel_hi:[1,0]
	v_mfma_f32_16x16x32_bf16 v[200:203], v[188:191], v[4:7], 0
	v_fma_f32 v186, v108, v186, v100
	v_fma_f32 v187, v109, v187, v101
	v_pk_mul_f32 v[174:175], v[174:175], v[170:171] op_sel_hi:[1,0]
	v_pk_mul_f32 v[172:173], v[172:173], v[170:171] op_sel_hi:[1,0]
	v_mfma_f32_16x16x32_bf16 v[196:199], v[188:191], v[0:3], v[196:199]
	v_mul_f32_e64 v178, v178, v170
	v_mul_f32_e64 v179, v179, v170
	v_pk_mul_f32 v[162:163], v[162:163], v[170:171] op_sel_hi:[1,0]
	v_pk_fma_f32 v[178:179], v[92:93], v[178:179], v[84:85]
	v_mfma_f32_16x16x32_bf16 v[188:191], v[188:191], v[48:51], v[200:203]
	v_mul_f32_e64 v160, v160, v170
	v_mul_f32_e64 v161, v161, v170
	v_pk_mul_f32 v[166:167], v[166:167], v[170:171] op_sel_hi:[1,0]
	v_add_u32_e32 v158, 16, v158
	v_mfma_f32_16x16x32_bf16 v[196:199], v[192:195], v[8:11], v[196:199]
	v_fma_f32 v166, v76, v166, v68
	v_fma_f32 v167, v77, v167, v69
	v_mfma_f32_16x16x32_bf16 v[188:191], v[192:195], v[4:7], v[188:191]
	v_fma_f32 v192, v104, v182, v96
	v_fma_f32 v193, v105, v183, v97
	v_pk_mul_f32 v[182:183], v[184:185], v[170:171] op_sel_hi:[1,0]
	v_mul_f32_e32 v157, 4.0, v192
	v_mul_f32_e32 v159, 4.0, v193
	v_mov_b32_e32 v184, v213
	v_cvt_pk_fp8_f32 v184, v157, v159
	v_pk_fma_f32 v[194:195], v[106:107], v[180:181], v[98:99]
	v_mov_b32_e32 v185, v213
	v_mul_f32_e32 v157, 4.0, v194
	v_mul_f32_e32 v159, 4.0, v195
	v_cvt_pk_fp8_f32 v184, v157, v159 op_sel:[0,0,1]
	v_mul_f32_e32 v157, 4.0, v186
	v_mul_f32_e32 v159, 4.0, v187
	v_cvt_pk_fp8_f32 v185, v157, v159
	v_pk_fma_f32 v[200:201], v[110:111], v[182:183], v[102:103]
	v_cvt_pk_bf16_f32 v180, v192, v193
	v_mul_f32_e32 v157, 4.0, v200
	v_mul_f32_e32 v159, 4.0, v201
	v_cvt_pk_fp8_f32 v185, v157, v159 op_sel:[0,0,1]
	v_cvt_pk_bf16_f32 v181, v194, v195
	v_cvt_pk_bf16_f32 v182, v186, v187
	v_cvt_pk_bf16_f32 v183, v200, v201
	global_store_dwordx2 v[168:169], v[184:185], off offset:32
	v_lshlrev_b32_e32 v184, 16, v180
	v_and_b32_e32 v185, 0xffff0000, v180
	v_pk_add_f32 v[184:185], v[192:193], v[184:185] neg_lo:[0,1] neg_hi:[0,1]
	v_lshlrev_b32_e32 v192, 16, v181
	v_and_b32_e32 v193, 0xffff0000, v181
	v_pk_add_f32 v[192:193], v[194:195], v[192:193] neg_lo:[0,1] neg_hi:[0,1]
	v_cvt_pk_bf16_f32 v184, v184, v185
	v_cvt_pk_bf16_f32 v185, v192, v193
	v_lshlrev_b32_e32 v192, 16, v182
	v_and_b32_e32 v193, 0xffff0000, v182
	v_pk_add_f32 v[186:187], v[186:187], v[192:193] neg_lo:[0,1] neg_hi:[0,1]
	v_lshlrev_b32_e32 v192, 16, v183
	v_and_b32_e32 v193, 0xffff0000, v183
	v_pk_add_f32 v[192:193], v[200:201], v[192:193] neg_lo:[0,1] neg_hi:[0,1]
	v_cvt_pk_bf16_f32 v186, v186, v187
	v_cvt_pk_bf16_f32 v187, v192, v193
	v_mfma_f32_16x16x32_bf16 v[192:195], v[180:183], v[12:15], v[196:199]
	v_mfma_f32_16x16x32_bf16 v[188:191], v[180:183], v[24:27], v[188:191]
	v_mfma_f32_16x16x32_bf16 v[192:195], v[180:183], v[16:19], v[192:195]
	v_mfma_f32_16x16x32_bf16 v[180:183], v[180:183], v[20:23], v[188:191]
	v_mfma_f32_16x16x32_bf16 v[192:195], v[184:187], v[12:15], v[192:195]
	v_mfma_f32_16x16x32_bf16 v[180:183], v[184:187], v[24:27], v[180:183]
	v_fma_f32 v184, v88, v174, v80
	v_fma_f32 v185, v89, v175, v81
	v_pk_mul_f32 v[174:175], v[176:177], v[170:171] op_sel_hi:[1,0]
	v_mul_f32_e32 v157, 4.0, v184
	v_mul_f32_e32 v159, 4.0, v185
	v_mov_b32_e32 v176, v213
	v_cvt_pk_fp8_f32 v176, v157, v159
	v_pk_fma_f32 v[186:187], v[90:91], v[172:173], v[82:83]
	v_mov_b32_e32 v177, v213
	v_mul_f32_e32 v157, 4.0, v186
	v_mul_f32_e32 v159, 4.0, v187
	v_cvt_pk_fp8_f32 v176, v157, v159 op_sel:[0,0,1]
	v_mul_f32_e32 v157, 4.0, v178
	v_mul_f32_e32 v159, 4.0, v179
	v_cvt_pk_fp8_f32 v177, v157, v159
	v_pk_fma_f32 v[188:189], v[94:95], v[174:175], v[86:87]
	v_cvt_pk_bf16_f32 v172, v184, v185
	v_mul_f32_e32 v157, 4.0, v188
	v_mul_f32_e32 v159, 4.0, v189
	v_cvt_pk_fp8_f32 v177, v157, v159 op_sel:[0,0,1]
	v_cvt_pk_bf16_f32 v173, v186, v187
	v_cvt_pk_bf16_f32 v174, v178, v179
	v_cvt_pk_bf16_f32 v175, v188, v189
	global_store_dwordx2 v[168:169], v[176:177], off offset:64
	v_lshlrev_b32_e32 v176, 16, v172
	v_and_b32_e32 v177, 0xffff0000, v172
	v_pk_add_f32 v[176:177], v[184:185], v[176:177] neg_lo:[0,1] neg_hi:[0,1]
	v_lshlrev_b32_e32 v184, 16, v173
	v_and_b32_e32 v185, 0xffff0000, v173
	v_pk_add_f32 v[184:185], v[186:187], v[184:185] neg_lo:[0,1] neg_hi:[0,1]
	v_cvt_pk_bf16_f32 v176, v176, v177
	v_cvt_pk_bf16_f32 v177, v184, v185
	v_lshlrev_b32_e32 v184, 16, v174
	v_and_b32_e32 v185, 0xffff0000, v174
	v_pk_add_f32 v[178:179], v[178:179], v[184:185] neg_lo:[0,1] neg_hi:[0,1]
	v_lshlrev_b32_e32 v184, 16, v175
	v_and_b32_e32 v185, 0xffff0000, v175
	v_pk_add_f32 v[184:185], v[188:189], v[184:185] neg_lo:[0,1] neg_hi:[0,1]
	v_cvt_pk_bf16_f32 v178, v178, v179
	v_cvt_pk_bf16_f32 v179, v184, v185
	v_mfma_f32_16x16x32_bf16 v[184:187], v[172:175], v[40:43], v[192:195]
	v_add_u32_e32 v188, 0x400, v222
	v_mfma_f32_16x16x32_bf16 v[180:183], v[172:175], v[28:31], v[180:183]
	v_mfma_f32_16x16x32_bf16 v[184:187], v[172:175], v[32:35], v[184:187]
	v_mfma_f32_16x16x32_bf16 v[172:175], v[172:175], v[36:39], v[180:183]
	v_mfma_f32_16x16x32_bf16 v[184:187], v[176:179], v[40:43], v[184:187]
	v_mfma_f32_16x16x32_bf16 v[172:175], v[176:179], v[28:31], v[172:175]
	v_fma_f32 v176, v72, v162, v64
	v_fma_f32 v177, v73, v163, v65
	v_pk_mul_f32 v[162:163], v[164:165], v[170:171] op_sel_hi:[1,0]
	v_mul_f32_e32 v157, 4.0, v176
	v_mul_f32_e32 v159, 4.0, v177
	v_mov_b32_e32 v164, v213
	v_cvt_pk_fp8_f32 v164, v157, v159
	v_pk_fma_f32 v[170:171], v[74:75], v[160:161], v[66:67]
	v_mov_b32_e32 v165, v213
	v_mul_f32_e32 v157, 4.0, v170
	v_mul_f32_e32 v159, 4.0, v171
	v_cvt_pk_fp8_f32 v164, v157, v159 op_sel:[0,0,1]
	v_mul_f32_e32 v157, 4.0, v166
	v_mul_f32_e32 v159, 4.0, v167
	v_cvt_pk_fp8_f32 v165, v157, v159
	v_pk_fma_f32 v[178:179], v[78:79], v[162:163], v[70:71]
	v_cvt_pk_bf16_f32 v160, v176, v177
	v_mul_f32_e32 v157, 4.0, v178
	v_mul_f32_e32 v159, 4.0, v179
	v_cvt_pk_fp8_f32 v165, v157, v159 op_sel:[0,0,1]
	v_cvt_pk_bf16_f32 v161, v170, v171
	v_cvt_pk_bf16_f32 v162, v166, v167
	v_cvt_pk_bf16_f32 v163, v178, v179
	global_store_dwordx2 v[168:169], v[164:165], off offset:96
	v_lshlrev_b32_e32 v164, 16, v160
	v_and_b32_e32 v165, 0xffff0000, v160
	v_lshlrev_b32_e32 v168, 16, v161
	v_and_b32_e32 v169, 0xffff0000, v161
	v_pk_add_f32 v[164:165], v[176:177], v[164:165] neg_lo:[0,1] neg_hi:[0,1]
	v_pk_add_f32 v[168:169], v[170:171], v[168:169] neg_lo:[0,1] neg_hi:[0,1]
	v_cvt_pk_bf16_f32 v164, v164, v165
	v_cvt_pk_bf16_f32 v165, v168, v169
	v_lshlrev_b32_e32 v168, 16, v162
	v_and_b32_e32 v169, 0xffff0000, v162
	v_pk_add_f32 v[166:167], v[166:167], v[168:169] neg_lo:[0,1] neg_hi:[0,1]
	v_lshlrev_b32_e32 v168, 16, v163
	v_and_b32_e32 v169, 0xffff0000, v163
	v_pk_add_f32 v[168:169], v[178:179], v[168:169] neg_lo:[0,1] neg_hi:[0,1]
	v_cvt_pk_bf16_f32 v166, v166, v167
	v_cvt_pk_bf16_f32 v167, v168, v169
	v_mfma_f32_16x16x32_bf16 v[168:171], v[160:163], v[44:47], v[184:187]
	v_add_u32_e32 v159, s22, v212
	s_addk_i32 s22, 0x840
	s_cmpk_eq_i32 s22, 0x39c0
	v_mfma_f32_16x16x32_bf16 v[172:175], v[160:163], v[52:55], v[172:175]
	v_mfma_f32_16x16x32_bf16 v[168:171], v[160:163], v[56:59], v[168:171]
	v_mfma_f32_16x16x32_bf16 v[160:163], v[160:163], v[60:63], v[172:175]
	v_mfma_f32_16x16x32_bf16 v[168:171], v[164:167], v[44:47], v[168:171]
	v_mfma_f32_16x16x32_bf16 v[160:163], v[164:167], v[52:55], v[160:163]
	s_nop 7
	ds_write2_b32 v188, v168, v160 offset1:16
	ds_write2_b32 v188, v169, v161 offset0:32 offset1:48
	ds_write2_b32 v188, v170, v162 offset0:64 offset1:80
	ds_write2_b32 v188, v171, v163 offset0:96 offset1:112
	s_waitcnt lgkmcnt(0)
	s_barrier
	ds_read2st64_b32 v[160:161], v216 offset0:4 offset1:12
	ds_read2st64_b32 v[244:245], v216 offset0:20 offset1:28
	ds_read2st64_b32 v[246:247], v216 offset0:36 offset1:44
	ds_read2st64_b32 v[248:249], v216 offset0:52 offset1:60
	s_waitcnt lgkmcnt(3)
	v_add_f32_e32 v157, v253, v160
	v_add_f32_e32 v157, v157, v161
	s_waitcnt lgkmcnt(2)
	v_add_f32_e32 v157, v157, v244
	v_add_f32_e32 v157, v157, v245
	s_waitcnt lgkmcnt(1)
	v_add_f32_e32 v157, v157, v246
	v_add_f32_e32 v157, v157, v247
	s_waitcnt lgkmcnt(0)
	v_add_f32_e32 v157, v157, v248
	v_add_f32_e32 v157, v157, v249
	ds_write_b32 v159, v157
	s_cbranch_scc1 .LBB0_807
